# speedup vs baseline: 1.0060x; 1.0027x over previous
; DI unsigned pk2(float lo, float hi) { unsigned r; asm("v_cvt_pk_bf16_f32 %0, %1, %2" : "=v"(r) : "v"(lo), "v"(hi)); return r; }
; DI void phase_prologue(CP& p, LAS unsigned char* lds) {
;     ...
;   for (int it = gw; it < NIT; it += NGW) {
;     int r = it;
;     if (r < 2 * I_LAYER) {
;       const int l = r / I_LAYER; r -= l * I_LAYER;
;       if (r < I_IN) { transpose_item(p.in[9] + (size_t)l * DM * INW, DM, INW, winT + (size_t)l * INW * DM, scr, r, lane); continue; } r -= I_IN;
;       if (r < 4 * I_B) { const int n = r / I_B; r -= n * I_B; transpose_item(p.in[23] + ((size_t)l * 4 + n) * 512 * DM, 512, DM, wbT + ((size_t)l * 4 + n) * DM * 512, scr, r, lane); continue; } r -= 4 * I_B;
;       if (r < I_O) { transpose_item(p.in[24] + (size_t)l * DM * DM, DM, DM, woutT + (size_t)l * DM * DM, scr, r, lane); continue; } r -= I_O;
;       transpose_item(p.in[19] + (size_t)l * DM * 1024, DM, 1024, wmemT + (size_t)l * 1024 * DM, scr, r, lane); continue;
;     }
;     r -= 2 * I_LAYER;
;     if (r < I_ROWS) {
;       if (r < TP) rms_row(p.in[0] + (size_t)r * DM, p.in[8], h + (size_t)r * DM, lane);
;       else if (r < TVAL) rms_row(p.in[1] + (size_t)(r - TP) * DM, p.in[8], h + (size_t)r * DM, lane);
;       else if (r < TALL) { u32x4* o = (u32x4*)(h + (size_t)r * DM); unsigned zz = 0u; asm volatile("" : "+v"(zz)); const u32x4 z = {zz, zz, zz, zz};
; #pragma unroll
;         for (int j = 0; j < 4; ++j) o[lane + 64 * j] = z; }
;       else { const int q = r - TALL, l = q >> 8, row = q & 255; rms_row(p.in[2] + (size_t)row * DM, p.in[18] + (size_t)l * DM, hm + ((size_t)l * 256 + row) * DM, lane); }
;       continue;
;     }
;     r -= I_ROWS;
;     for (int e = lane; e < 2048; e += 64) { const int idx = r * 2048 + e, i = (idx >> 7) & 127, j = idx & 127;
;       const float v = ((j >> 6) <= (i >> 6)) ? p.in[12][idx] : 0.f; wsb[idx] = (u16)(pk2(v, 0.f) & 0xffffu); }
;   }
.LBB0_360:
	s_mov_b32 s0, 0x97ff
	v_cmp_lt_i32_e32 vcc, s0, v33
	s_and_saveexec_b64 s[14:15], vcc
	s_xor_b64 s[16:17], exec, s[14:15]
	s_cbranch_execz .LBB0_382
	s_mov_b32 s0, 0xdaff
	v_cmp_lt_u32_e32 vcc, s0, v33
	s_and_saveexec_b64 s[14:15], vcc
	s_xor_b64 s[24:25], exec, s[14:15]
	s_cbranch_execz .LBB0_367
	v_bfe_u32 v2, v33, 2, 1
	s_mov_b64 s[26:27], 0
	s_mov_b32 s0, 0xf9280040
	v_add3_u32 v0, v91, v90, s0
	v_ashrrev_i32_e32 v1, 31, v0
	v_lshl_add_u64 v[6:7], v[0:1], 2, s[64:65]
	v_lshl_add_u64 v[0:1], v[0:1], 1, s[12:13]
	v_add_co_u32_e32 v8, vcc, 0x1000, v6
	s_nop 1
	v_addc_co_u32_e32 v9, vcc, 0, v7, vcc
	v_mov_b32_e32 v93, 0
	v_mov_b32_e32 v95, 0
	v_mov_b32_e32 v97, 0
	v_mov_b32_e32 v99, 0
	v_mov_b32_e32 v101, 0
	v_mov_b32_e32 v103, 0
	v_mov_b32_e32 v105, 0
	v_mov_b32_e32 v107, 0
	v_mov_b32_e32 v109, 0
	v_mov_b32_e32 v111, 0
	v_mov_b32_e32 v113, 0
	v_mov_b32_e32 v115, 0
	v_mov_b32_e32 v117, 0
	v_mov_b32_e32 v119, 0
	v_mov_b32_e32 v121, 0
	v_mov_b32_e32 v123, 0
	global_load_dword v92, v[6:7], off
	global_load_dword v94, v[6:7], off offset:512
	global_load_dword v96, v[6:7], off offset:1024
	global_load_dword v98, v[6:7], off offset:1536
	global_load_dword v100, v[6:7], off offset:2048
	global_load_dword v102, v[6:7], off offset:2560
	global_load_dword v104, v[6:7], off offset:3072
	global_load_dword v106, v[6:7], off offset:3584
	global_load_dword v108, v[8:9], off
	global_load_dword v110, v[8:9], off offset:512
	global_load_dword v112, v[8:9], off offset:1024
	global_load_dword v114, v[8:9], off offset:1536
	global_load_dword v116, v[8:9], off offset:2048
	global_load_dword v118, v[8:9], off offset:2560
	global_load_dword v120, v[8:9], off offset:3072
	global_load_dword v122, v[8:9], off offset:3584
	v_cmp_ne_u32_e32 vcc, 0, v2
	s_and_saveexec_b64 s[58:59], vcc
	global_load_dword v93, v[6:7], off offset:256
	global_load_dword v95, v[6:7], off offset:768
	global_load_dword v97, v[6:7], off offset:1280
	global_load_dword v99, v[6:7], off offset:1792
	global_load_dword v101, v[6:7], off offset:2304
	global_load_dword v103, v[6:7], off offset:2816
	global_load_dword v105, v[6:7], off offset:3328
	global_load_dword v107, v[6:7], off offset:3840
	global_load_dword v109, v[8:9], off offset:256
	global_load_dword v111, v[8:9], off offset:768
	global_load_dword v113, v[8:9], off offset:1280
	global_load_dword v115, v[8:9], off offset:1792
	global_load_dword v117, v[8:9], off offset:2304
	global_load_dword v119, v[8:9], off offset:2816
	global_load_dword v121, v[8:9], off offset:3328
	global_load_dword v123, v[8:9], off offset:3840
	s_or_b64 exec, exec, s[58:59]
	s_waitcnt vmcnt(0)
	v_cvt_pk_bf16_f32 v92, v92, v147
	v_cvt_pk_bf16_f32 v93, v93, v147
	v_cvt_pk_bf16_f32 v94, v94, v147
	v_cvt_pk_bf16_f32 v95, v95, v147
	v_cvt_pk_bf16_f32 v96, v96, v147
	v_cvt_pk_bf16_f32 v97, v97, v147
	v_cvt_pk_bf16_f32 v98, v98, v147
	v_cvt_pk_bf16_f32 v99, v99, v147
	v_cvt_pk_bf16_f32 v100, v100, v147
	v_cvt_pk_bf16_f32 v101, v101, v147
	v_cvt_pk_bf16_f32 v102, v102, v147
	v_cvt_pk_bf16_f32 v103, v103, v147
	v_cvt_pk_bf16_f32 v104, v104, v147
	v_cvt_pk_bf16_f32 v105, v105, v147
	v_cvt_pk_bf16_f32 v106, v106, v147
	v_cvt_pk_bf16_f32 v107, v107, v147
	v_cvt_pk_bf16_f32 v108, v108, v147
	v_cvt_pk_bf16_f32 v109, v109, v147
	v_cvt_pk_bf16_f32 v110, v110, v147
	v_cvt_pk_bf16_f32 v111, v111, v147
	v_cvt_pk_bf16_f32 v112, v112, v147
	v_cvt_pk_bf16_f32 v113, v113, v147
	v_cvt_pk_bf16_f32 v114, v114, v147
	v_cvt_pk_bf16_f32 v115, v115, v147
	v_cvt_pk_bf16_f32 v116, v116, v147
	v_cvt_pk_bf16_f32 v117, v117, v147
	v_cvt_pk_bf16_f32 v118, v118, v147
	v_cvt_pk_bf16_f32 v119, v119, v147
	v_cvt_pk_bf16_f32 v120, v120, v147
	v_cvt_pk_bf16_f32 v121, v121, v147
	v_cvt_pk_bf16_f32 v122, v122, v147
	v_cvt_pk_bf16_f32 v123, v123, v147
	global_store_short v[0:1], v92, off
	global_store_short v[0:1], v93, off offset:128
	global_store_short v[0:1], v94, off offset:256
	global_store_short v[0:1], v95, off offset:384
	global_store_short v[0:1], v96, off offset:512
	global_store_short v[0:1], v97, off offset:640
	global_store_short v[0:1], v98, off offset:768
	global_store_short v[0:1], v99, off offset:896
	global_store_short v[0:1], v100, off offset:1024
	global_store_short v[0:1], v101, off offset:1152
	global_store_short v[0:1], v102, off offset:1280
	global_store_short v[0:1], v103, off offset:1408
	global_store_short v[0:1], v104, off offset:1536
	global_store_short v[0:1], v105, off offset:1664
	global_store_short v[0:1], v106, off offset:1792
	global_store_short v[0:1], v107, off offset:1920
	global_store_short v[0:1], v108, off offset:2048
	global_store_short v[0:1], v109, off offset:2176
	global_store_short v[0:1], v110, off offset:2304
	global_store_short v[0:1], v111, off offset:2432
	global_store_short v[0:1], v112, off offset:2560
	global_store_short v[0:1], v113, off offset:2688
	global_store_short v[0:1], v114, off offset:2816
	global_store_short v[0:1], v115, off offset:2944
	global_store_short v[0:1], v116, off offset:3072
	global_store_short v[0:1], v117, off offset:3200
	global_store_short v[0:1], v118, off offset:3328
	global_store_short v[0:1], v119, off offset:3456
	global_store_short v[0:1], v120, off offset:3584
	global_store_short v[0:1], v121, off offset:3712
	global_store_short v[0:1], v122, off offset:3840
	global_store_short v[0:1], v123, off offset:3968
